# v12 + ret_inproj rope-table loads hoisted (one batched wait instead of 32 serialized) + out-projection residual epilogues de-serialised (all residual/gate loads issued up front, registers renamed)
# speedup vs baseline: 1.0636x; 1.0126x over previous
.LBB0_880:
	v_readlane_b32 s1, v180, 10
	s_add_i32 s0, s0, s1
	s_mulk_i32 s0, 0xc00
	s_ashr_i32 s1, s0, 31
	v_readlane_b32 s40, v183, 1
	s_lshl_b64 s[0:1], s[0:1], 2
	v_readlane_b32 s54, v183, 15
	v_readlane_b32 s55, v183, 16
	s_add_u32 s0, s54, s0
	s_addc_u32 s1, s55, s1
	s_add_u32 s0, s0, 0x4002000
	v_or_b32_e32 v86, s20, v91
	s_addc_u32 s1, s1, 0
	s_lshl_b64 s[8:9], s[8:9], 12
	v_ashrrev_i32_e32 v87, 31, v86
	s_add_u32 s10, s10, s8
	v_lshl_add_u64 v[88:89], v[76:77], 0, v[86:87]
	s_addc_u32 s11, s11, s9
	v_lshl_add_u64 v[98:99], v[86:87], 2, s[0:1]
	v_lshlrev_b64 v[100:101], 2, v[88:89]
	v_lshl_add_u64 v[88:89], s[10:11], 0, v[100:101]
	global_load_dwordx4 v[120:123], v[98:99], off
	s_nop 0
	global_load_dwordx4 v[124:127], v[88:89], off
	s_add_u32 s8, s36, s8
	v_lshl_add_u64 v[98:99], v[78:79], 0, v[86:87]
	s_addc_u32 s9, s37, s9
	v_lshlrev_b64 v[102:103], 2, v[98:99]
	v_lshl_add_u64 v[98:99], s[8:9], 0, v[100:101]
	v_lshl_add_u64 v[100:101], s[10:11], 0, v[102:103]
	v_lshl_add_u64 v[128:129], s[8:9], 0, v[102:103]
	v_readlane_b32 s52, v183, 13
	v_readlane_b32 s53, v183, 14
	v_readlane_b32 s48, v183, 9
	v_readlane_b32 s50, v183, 11
	v_readlane_b32 s51, v183, 12
	s_add_i32 s12, s12, s84
	v_readlane_b32 s22, v183, 63
	v_readlane_b32 s52, v181, 60
	v_readlane_b32 s23, v182, 0
	v_readlane_b32 s50, v180, 0
	v_readlane_b32 s53, v181, 61
	v_readlane_b32 s54, v181, 62
	v_readlane_b32 s55, v181, 63
	s_mov_b32 s48, s5
	v_readlane_b32 s41, v183, 2
	v_readlane_b32 s42, v183, 3
	v_readlane_b32 s43, v183, 4
	v_readlane_b32 s44, v183, 5
	v_readlane_b32 s45, v183, 6
	v_readlane_b32 s46, v183, 7
	v_readlane_b32 s47, v183, 8
	v_readlane_b32 s49, v183, 10
	v_readlane_b32 s51, v180, 1
	global_load_dwordx4 v[130:133], v[100:101], off
	v_lshl_add_u64 v[102:103], v[80:81], 0, v[86:87]
	v_lshlrev_b64 v[134:135], 2, v[102:103]
	v_lshl_add_u64 v[102:103], s[10:11], 0, v[134:135]
	v_lshl_add_u64 v[136:137], s[8:9], 0, v[134:135]
	global_load_dwordx4 v[138:141], v[102:103], off
	v_lshl_add_u64 v[134:135], v[82:83], 0, v[86:87]
	v_lshlrev_b64 v[142:143], 2, v[134:135]
	v_lshl_add_u64 v[134:135], s[10:11], 0, v[142:143]
	global_load_dwordx4 v[144:147], v[134:135], off
	v_or_b32_e32 v148, 16, v86
	v_ashrrev_i32_e32 v149, 31, v148
	v_lshl_add_u64 v[150:151], s[8:9], 0, v[142:143]
	v_lshl_add_u64 v[142:143], v[148:149], 2, s[0:1]
	global_load_dwordx4 v[152:155], v[142:143], off
	s_nop 0
	global_load_dwordx4 v[156:159], v[88:89], off offset:64
	global_load_dwordx4 v[160:163], v[100:101], off offset:64
	global_load_dwordx4 v[164:167], v[102:103], off offset:64
	global_load_dwordx4 v[168:171], v[134:135], off offset:64
	v_or_b32_e32 v142, 32, v86
	v_ashrrev_i32_e32 v143, 31, v142
	v_lshl_add_u64 v[148:149], v[142:143], 2, s[0:1]
	global_load_dwordx4 v[172:175], v[148:149], off
	s_nop 0
	global_load_dwordx4 v[176:179], v[88:89], off offset:128
	global_load_dwordx4 v[184:187], v[100:101], off offset:128
	global_load_dwordx4 v[188:191], v[102:103], off offset:128
	global_load_dwordx4 v[192:195], v[134:135], off offset:128
	v_or_b32_e32 v142, 48, v86
	v_ashrrev_i32_e32 v143, 31, v142
	v_lshl_add_u64 v[86:87], v[142:143], 2, s[0:1]
	v_readlane_b32 s0, v180, 7
	s_cmp_lt_i32 s12, s0
	global_load_dwordx4 v[196:199], v[86:87], off
	s_nop 0
	global_load_dwordx4 v[200:203], v[88:89], off offset:192
	global_load_dwordx4 v[86:89], v[100:101], off offset:192
	global_load_dwordx4 v[204:207], v[102:103], off offset:192
	global_load_dwordx4 v[100:103], v[134:135], off offset:192
	s_waitcnt vmcnt(0)
	v_pk_fma_f32 v[60:61], v[60:61], v[120:121], v[124:125]
	v_pk_fma_f32 v[62:63], v[62:63], v[122:123], v[126:127]
	global_store_dwordx4 v[98:99], v[60:63], off
	v_pk_fma_f32 v[56:57], v[56:57], v[120:121], v[130:131]
	v_pk_fma_f32 v[58:59], v[58:59], v[122:123], v[132:133]
	global_store_dwordx4 v[128:129], v[56:59], off
	v_pk_fma_f32 v[52:53], v[52:53], v[120:121], v[138:139]
	v_pk_fma_f32 v[54:55], v[54:55], v[122:123], v[140:141]
	global_store_dwordx4 v[136:137], v[52:55], off
	v_pk_fma_f32 v[48:49], v[48:49], v[120:121], v[144:145]
	v_pk_fma_f32 v[50:51], v[50:51], v[122:123], v[146:147]
	global_store_dwordx4 v[150:151], v[48:51], off
	v_pk_fma_f32 v[44:45], v[44:45], v[152:153], v[156:157]
	v_pk_fma_f32 v[46:47], v[46:47], v[154:155], v[158:159]
	global_store_dwordx4 v[98:99], v[44:47], off offset:64
	v_pk_fma_f32 v[40:41], v[40:41], v[152:153], v[160:161]
	v_pk_fma_f32 v[42:43], v[42:43], v[154:155], v[162:163]
	global_store_dwordx4 v[128:129], v[40:43], off offset:64
	v_pk_fma_f32 v[36:37], v[36:37], v[152:153], v[164:165]
	v_pk_fma_f32 v[38:39], v[38:39], v[154:155], v[166:167]
	global_store_dwordx4 v[136:137], v[36:39], off offset:64
	v_pk_fma_f32 v[32:33], v[32:33], v[152:153], v[168:169]
	v_pk_fma_f32 v[34:35], v[34:35], v[154:155], v[170:171]
	global_store_dwordx4 v[150:151], v[32:35], off offset:64
	v_pk_fma_f32 v[28:29], v[28:29], v[172:173], v[176:177]
	v_pk_fma_f32 v[30:31], v[30:31], v[174:175], v[178:179]
	global_store_dwordx4 v[98:99], v[28:31], off offset:128
	v_pk_fma_f32 v[24:25], v[24:25], v[172:173], v[184:185]
	v_pk_fma_f32 v[26:27], v[26:27], v[174:175], v[186:187]
	global_store_dwordx4 v[128:129], v[24:27], off offset:128
	v_pk_fma_f32 v[20:21], v[20:21], v[172:173], v[188:189]
	v_pk_fma_f32 v[22:23], v[22:23], v[174:175], v[190:191]
	global_store_dwordx4 v[136:137], v[20:23], off offset:128
	v_pk_fma_f32 v[16:17], v[16:17], v[172:173], v[192:193]
	v_pk_fma_f32 v[18:19], v[18:19], v[174:175], v[194:195]
	global_store_dwordx4 v[150:151], v[16:19], off offset:128
	v_pk_fma_f32 v[12:13], v[12:13], v[196:197], v[200:201]
	v_pk_fma_f32 v[14:15], v[14:15], v[198:199], v[202:203]
	global_store_dwordx4 v[98:99], v[12:15], off offset:192
	v_pk_fma_f32 v[8:9], v[8:9], v[196:197], v[86:87]
	v_pk_fma_f32 v[10:11], v[10:11], v[198:199], v[88:89]
	global_store_dwordx4 v[128:129], v[8:11], off offset:192
	v_pk_fma_f32 v[4:5], v[4:5], v[196:197], v[204:205]
	v_pk_fma_f32 v[6:7], v[6:7], v[198:199], v[206:207]
	global_store_dwordx4 v[136:137], v[4:7], off offset:192
	v_pk_fma_f32 v[0:1], v[0:1], v[196:197], v[100:101]
	v_pk_fma_f32 v[2:3], v[2:3], v[198:199], v[102:103]
	global_store_dwordx4 v[150:151], v[0:3], off offset:192
	s_cbranch_scc0 .LBB0_888

.LBB0_907:
	s_cmp_lt_u32 s8, 8
	s_cselect_b64 s[0:1], -1, 0
	s_cmp_gt_u32 s8, 7
	s_cselect_b64 s[44:45], -1, 0
	s_bfe_u32 s9, s24, 0x20008
	s_or_b32 s9, s9, s48
	s_lshl_b32 s9, s9, 2
	v_mov_b32_e32 v68, s9
	global_load_dword v89, v68, s[58:59]
	global_load_dword v88, v68, s[58:59] offset:16
	s_lshl_b32 s9, s8, 6
	v_cndmask_b32_e64 v82, v115, 1.0, s[0:1]
	v_and_or_b32 v146, s9, 64, v132
	s_bitcmp1_b32 s8, 0
	v_mov_b32_e32 v84, v60
	v_mov_b32_e32 v85, v56
	v_cndmask_b32_e64 v56, 0, 1, s[42:43]
	s_cselect_b64 s[40:41], -1, 0
	v_subrev_u32_e32 v154, 64, v146
	v_pk_mul_f32 v[84:85], v[82:83], v[84:85] op_sel_hi:[0,1]
	v_cmp_ne_u32_e64 s[36:37], 1, v56
	s_andn2_b64 vcc, exec, s[42:43]
	v_add_u32_e32 v145, s10, v76
	s_cbranch_vccnz .Lrope_pre_skip
	v_or_b32_e32 v250, 16, v132
	s_and_b64 vcc, exec, s[40:41]
	s_cbranch_vccz .Lrope_pre_B
	v_add_u32_e32 v248, s10, v76
	v_and_b32_e32 v249, 63, v248
	v_lshl_or_b32 v249, v249, 6, v132
	v_lshlrev_b32_e32 v249, 3, v249
	global_load_dwordx2 v[184:185], v249, s[82:83]
	v_add_u32_e32 v248, s10, v76
	v_add_u32_e32 v248, 1, v248
	v_and_b32_e32 v249, 63, v248
	v_lshl_or_b32 v249, v249, 6, v132
	v_lshlrev_b32_e32 v249, 3, v249
	global_load_dwordx2 v[186:187], v249, s[82:83]
	v_add_u32_e32 v248, s10, v76
	v_add_u32_e32 v248, 2, v248
	v_and_b32_e32 v249, 63, v248
	v_lshl_or_b32 v249, v249, 6, v132
	v_lshlrev_b32_e32 v249, 3, v249
	global_load_dwordx2 v[188:189], v249, s[82:83]
	v_add_u32_e32 v248, s10, v76
	v_add_u32_e32 v248, 3, v248
	v_and_b32_e32 v249, 63, v248
	v_lshl_or_b32 v249, v249, 6, v132
	v_lshlrev_b32_e32 v249, 3, v249
	global_load_dwordx2 v[190:191], v249, s[82:83]
	v_add_u32_e32 v248, s10, v129
	v_and_b32_e32 v249, 63, v248
	v_lshl_or_b32 v249, v249, 6, v132
	v_lshlrev_b32_e32 v249, 3, v249
	global_load_dwordx2 v[192:193], v249, s[82:83]
	v_add_u32_e32 v248, s10, v129
	v_add_u32_e32 v248, 1, v248
	v_and_b32_e32 v249, 63, v248
	v_lshl_or_b32 v249, v249, 6, v132
	v_lshlrev_b32_e32 v249, 3, v249
	global_load_dwordx2 v[194:195], v249, s[82:83]
	v_add_u32_e32 v248, s10, v129
	v_add_u32_e32 v248, 2, v248
	v_and_b32_e32 v249, 63, v248
	v_lshl_or_b32 v249, v249, 6, v132
	v_lshlrev_b32_e32 v249, 3, v249
	global_load_dwordx2 v[196:197], v249, s[82:83]
	v_add_u32_e32 v248, s10, v129
	v_add_u32_e32 v248, 3, v248
	v_and_b32_e32 v249, 63, v248
	v_lshl_or_b32 v249, v249, 6, v132
	v_lshlrev_b32_e32 v249, 3, v249
	global_load_dwordx2 v[198:199], v249, s[82:83]
	v_add_u32_e32 v248, s10, v130
	v_and_b32_e32 v249, 63, v248
	v_lshl_or_b32 v249, v249, 6, v132
	v_lshlrev_b32_e32 v249, 3, v249
	global_load_dwordx2 v[200:201], v249, s[82:83]
	v_add_u32_e32 v248, s10, v130
	v_add_u32_e32 v248, 1, v248
	v_and_b32_e32 v249, 63, v248
	v_lshl_or_b32 v249, v249, 6, v132
	v_lshlrev_b32_e32 v249, 3, v249
	global_load_dwordx2 v[202:203], v249, s[82:83]
	v_add_u32_e32 v248, s10, v130
	v_add_u32_e32 v248, 2, v248
	v_and_b32_e32 v249, 63, v248
	v_lshl_or_b32 v249, v249, 6, v132
	v_lshlrev_b32_e32 v249, 3, v249
	global_load_dwordx2 v[204:205], v249, s[82:83]
	v_add_u32_e32 v248, s10, v130
	v_add_u32_e32 v248, 3, v248
	v_and_b32_e32 v249, 63, v248
	v_lshl_or_b32 v249, v249, 6, v132
	v_lshlrev_b32_e32 v249, 3, v249
	global_load_dwordx2 v[206:207], v249, s[82:83]
	v_add_u32_e32 v248, s10, v131
	v_and_b32_e32 v249, 63, v248
	v_lshl_or_b32 v249, v249, 6, v132
	v_lshlrev_b32_e32 v249, 3, v249
	global_load_dwordx2 v[208:209], v249, s[82:83]
	v_add_u32_e32 v248, s10, v131
	v_add_u32_e32 v248, 1, v248
	v_and_b32_e32 v249, 63, v248
	v_lshl_or_b32 v249, v249, 6, v132
	v_lshlrev_b32_e32 v249, 3, v249
	global_load_dwordx2 v[210:211], v249, s[82:83]
	v_add_u32_e32 v248, s10, v131
	v_add_u32_e32 v248, 2, v248
	v_and_b32_e32 v249, 63, v248
	v_lshl_or_b32 v249, v249, 6, v132
	v_lshlrev_b32_e32 v249, 3, v249
	global_load_dwordx2 v[212:213], v249, s[82:83]
	v_add_u32_e32 v248, s10, v131
	v_add_u32_e32 v248, 3, v248
	v_and_b32_e32 v249, 63, v248
	v_lshl_or_b32 v249, v249, 6, v132
	v_lshlrev_b32_e32 v249, 3, v249
	global_load_dwordx2 v[214:215], v249, s[82:83]
	v_add_u32_e32 v248, s10, v76
	v_and_b32_e32 v249, 63, v248
	v_lshl_or_b32 v249, v249, 6, v250
	v_lshlrev_b32_e32 v249, 3, v249
	global_load_dwordx2 v[216:217], v249, s[82:83]
	v_add_u32_e32 v248, s10, v76
	v_add_u32_e32 v248, 1, v248
	v_and_b32_e32 v249, 63, v248
	v_lshl_or_b32 v249, v249, 6, v250
	v_lshlrev_b32_e32 v249, 3, v249
	global_load_dwordx2 v[218:219], v249, s[82:83]
	v_add_u32_e32 v248, s10, v76
	v_add_u32_e32 v248, 2, v248
	v_and_b32_e32 v249, 63, v248
	v_lshl_or_b32 v249, v249, 6, v250
	v_lshlrev_b32_e32 v249, 3, v249
	global_load_dwordx2 v[220:221], v249, s[82:83]
	v_add_u32_e32 v248, s10, v76
	v_add_u32_e32 v248, 3, v248
	v_and_b32_e32 v249, 63, v248
	v_lshl_or_b32 v249, v249, 6, v250
	v_lshlrev_b32_e32 v249, 3, v249
	global_load_dwordx2 v[222:223], v249, s[82:83]
	v_add_u32_e32 v248, s10, v129
	v_and_b32_e32 v249, 63, v248
	v_lshl_or_b32 v249, v249, 6, v250
	v_lshlrev_b32_e32 v249, 3, v249
	global_load_dwordx2 v[224:225], v249, s[82:83]
	v_add_u32_e32 v248, s10, v129
	v_add_u32_e32 v248, 1, v248
	v_and_b32_e32 v249, 63, v248
	v_lshl_or_b32 v249, v249, 6, v250
	v_lshlrev_b32_e32 v249, 3, v249
	global_load_dwordx2 v[226:227], v249, s[82:83]
	v_add_u32_e32 v248, s10, v129
	v_add_u32_e32 v248, 2, v248
	v_and_b32_e32 v249, 63, v248
	v_lshl_or_b32 v249, v249, 6, v250
	v_lshlrev_b32_e32 v249, 3, v249
	global_load_dwordx2 v[228:229], v249, s[82:83]
	v_add_u32_e32 v248, s10, v129
	v_add_u32_e32 v248, 3, v248
	v_and_b32_e32 v249, 63, v248
	v_lshl_or_b32 v249, v249, 6, v250
	v_lshlrev_b32_e32 v249, 3, v249
	global_load_dwordx2 v[230:231], v249, s[82:83]
	v_add_u32_e32 v248, s10, v130
	v_and_b32_e32 v249, 63, v248
	v_lshl_or_b32 v249, v249, 6, v250
	v_lshlrev_b32_e32 v249, 3, v249
	global_load_dwordx2 v[232:233], v249, s[82:83]
	v_add_u32_e32 v248, s10, v130
	v_add_u32_e32 v248, 1, v248
	v_and_b32_e32 v249, 63, v248
	v_lshl_or_b32 v249, v249, 6, v250
	v_lshlrev_b32_e32 v249, 3, v249
	global_load_dwordx2 v[234:235], v249, s[82:83]
	v_add_u32_e32 v248, s10, v130
	v_add_u32_e32 v248, 2, v248
	v_and_b32_e32 v249, 63, v248
	v_lshl_or_b32 v249, v249, 6, v250
	v_lshlrev_b32_e32 v249, 3, v249
	global_load_dwordx2 v[236:237], v249, s[82:83]
	v_add_u32_e32 v248, s10, v130
	v_add_u32_e32 v248, 3, v248
	v_and_b32_e32 v249, 63, v248
	v_lshl_or_b32 v249, v249, 6, v250
	v_lshlrev_b32_e32 v249, 3, v249
	global_load_dwordx2 v[238:239], v249, s[82:83]
	v_add_u32_e32 v248, s10, v131
	v_and_b32_e32 v249, 63, v248
	v_lshl_or_b32 v249, v249, 6, v250
	v_lshlrev_b32_e32 v249, 3, v249
	global_load_dwordx2 v[240:241], v249, s[82:83]
	v_add_u32_e32 v248, s10, v131
	v_add_u32_e32 v248, 1, v248
	v_and_b32_e32 v249, 63, v248
	v_lshl_or_b32 v249, v249, 6, v250
	v_lshlrev_b32_e32 v249, 3, v249
	global_load_dwordx2 v[242:243], v249, s[82:83]
	v_add_u32_e32 v248, s10, v131
	v_add_u32_e32 v248, 2, v248
	v_and_b32_e32 v249, 63, v248
	v_lshl_or_b32 v249, v249, 6, v250
	v_lshlrev_b32_e32 v249, 3, v249
	global_load_dwordx2 v[244:245], v249, s[82:83]
	v_add_u32_e32 v248, s10, v131
	v_add_u32_e32 v248, 3, v248
	v_and_b32_e32 v249, 63, v248
	v_lshl_or_b32 v249, v249, 6, v250
	v_lshlrev_b32_e32 v249, 3, v249
	global_load_dwordx2 v[246:247], v249, s[82:83]
	s_branch .Lrope_pre_done
.Lrope_pre_B:
	v_add_u32_e32 v248, s10, v76
	v_and_b32_e32 v249, 0xffc0, v248
	v_or_b32_e32 v249, v249, v132
	v_lshlrev_b32_e32 v249, 3, v249
	global_load_dwordx2 v[184:185], v249, s[82:83]
	v_add_u32_e32 v248, s10, v76
	v_add_u32_e32 v248, 1, v248
	v_and_b32_e32 v249, 0xffc0, v248
	v_or_b32_e32 v249, v249, v132
	v_lshlrev_b32_e32 v249, 3, v249
	global_load_dwordx2 v[186:187], v249, s[82:83]
	v_add_u32_e32 v248, s10, v76
	v_add_u32_e32 v248, 2, v248
	v_and_b32_e32 v249, 0xffc0, v248
	v_or_b32_e32 v249, v249, v132
	v_lshlrev_b32_e32 v249, 3, v249
	global_load_dwordx2 v[188:189], v249, s[82:83]
	v_add_u32_e32 v248, s10, v76
	v_add_u32_e32 v248, 3, v248
	v_and_b32_e32 v249, 0xffc0, v248
	v_or_b32_e32 v249, v249, v132
	v_lshlrev_b32_e32 v249, 3, v249
	global_load_dwordx2 v[190:191], v249, s[82:83]
	v_add_u32_e32 v248, s10, v129
	v_and_b32_e32 v249, 0xffc0, v248
	v_or_b32_e32 v249, v249, v132
	v_lshlrev_b32_e32 v249, 3, v249
	global_load_dwordx2 v[192:193], v249, s[82:83]
	v_add_u32_e32 v248, s10, v129
	v_add_u32_e32 v248, 1, v248
	v_and_b32_e32 v249, 0xffc0, v248
	v_or_b32_e32 v249, v249, v132
	v_lshlrev_b32_e32 v249, 3, v249
	global_load_dwordx2 v[194:195], v249, s[82:83]
	v_add_u32_e32 v248, s10, v129
	v_add_u32_e32 v248, 2, v248
	v_and_b32_e32 v249, 0xffc0, v248
	v_or_b32_e32 v249, v249, v132
	v_lshlrev_b32_e32 v249, 3, v249
	global_load_dwordx2 v[196:197], v249, s[82:83]
	v_add_u32_e32 v248, s10, v129
	v_add_u32_e32 v248, 3, v248
	v_and_b32_e32 v249, 0xffc0, v248
	v_or_b32_e32 v249, v249, v132
	v_lshlrev_b32_e32 v249, 3, v249
	global_load_dwordx2 v[198:199], v249, s[82:83]
	v_add_u32_e32 v248, s10, v130
	v_and_b32_e32 v249, 0xffc0, v248
	v_or_b32_e32 v249, v249, v132
	v_lshlrev_b32_e32 v249, 3, v249
	global_load_dwordx2 v[200:201], v249, s[82:83]
	v_add_u32_e32 v248, s10, v130
	v_add_u32_e32 v248, 1, v248
	v_and_b32_e32 v249, 0xffc0, v248
	v_or_b32_e32 v249, v249, v132
	v_lshlrev_b32_e32 v249, 3, v249
	global_load_dwordx2 v[202:203], v249, s[82:83]
	v_add_u32_e32 v248, s10, v130
	v_add_u32_e32 v248, 2, v248
	v_and_b32_e32 v249, 0xffc0, v248
	v_or_b32_e32 v249, v249, v132
	v_lshlrev_b32_e32 v249, 3, v249
	global_load_dwordx2 v[204:205], v249, s[82:83]
	v_add_u32_e32 v248, s10, v130
	v_add_u32_e32 v248, 3, v248
	v_and_b32_e32 v249, 0xffc0, v248
	v_or_b32_e32 v249, v249, v132
	v_lshlrev_b32_e32 v249, 3, v249
	global_load_dwordx2 v[206:207], v249, s[82:83]
	v_add_u32_e32 v248, s10, v131
	v_and_b32_e32 v249, 0xffc0, v248
	v_or_b32_e32 v249, v249, v132
	v_lshlrev_b32_e32 v249, 3, v249
	global_load_dwordx2 v[208:209], v249, s[82:83]
	v_add_u32_e32 v248, s10, v131
	v_add_u32_e32 v248, 1, v248
	v_and_b32_e32 v249, 0xffc0, v248
	v_or_b32_e32 v249, v249, v132
	v_lshlrev_b32_e32 v249, 3, v249
	global_load_dwordx2 v[210:211], v249, s[82:83]
	v_add_u32_e32 v248, s10, v131
	v_add_u32_e32 v248, 2, v248
	v_and_b32_e32 v249, 0xffc0, v248
	v_or_b32_e32 v249, v249, v132
	v_lshlrev_b32_e32 v249, 3, v249
	global_load_dwordx2 v[212:213], v249, s[82:83]
	v_add_u32_e32 v248, s10, v131
	v_add_u32_e32 v248, 3, v248
	v_and_b32_e32 v249, 0xffc0, v248
	v_or_b32_e32 v249, v249, v132
	v_lshlrev_b32_e32 v249, 3, v249
	global_load_dwordx2 v[214:215], v249, s[82:83]
	v_add_u32_e32 v248, s10, v76
	v_and_b32_e32 v249, 0xffc0, v248
	v_or_b32_e32 v249, v249, v250
	v_lshlrev_b32_e32 v249, 3, v249
	global_load_dwordx2 v[216:217], v249, s[82:83]
	v_add_u32_e32 v248, s10, v76
	v_add_u32_e32 v248, 1, v248
	v_and_b32_e32 v249, 0xffc0, v248
	v_or_b32_e32 v249, v249, v250
	v_lshlrev_b32_e32 v249, 3, v249
	global_load_dwordx2 v[218:219], v249, s[82:83]
	v_add_u32_e32 v248, s10, v76
	v_add_u32_e32 v248, 2, v248
	v_and_b32_e32 v249, 0xffc0, v248
	v_or_b32_e32 v249, v249, v250
	v_lshlrev_b32_e32 v249, 3, v249
	global_load_dwordx2 v[220:221], v249, s[82:83]
	v_add_u32_e32 v248, s10, v76
	v_add_u32_e32 v248, 3, v248
	v_and_b32_e32 v249, 0xffc0, v248
	v_or_b32_e32 v249, v249, v250
	v_lshlrev_b32_e32 v249, 3, v249
	global_load_dwordx2 v[222:223], v249, s[82:83]
	v_add_u32_e32 v248, s10, v129
	v_and_b32_e32 v249, 0xffc0, v248
	v_or_b32_e32 v249, v249, v250
	v_lshlrev_b32_e32 v249, 3, v249
	global_load_dwordx2 v[224:225], v249, s[82:83]
	v_add_u32_e32 v248, s10, v129
	v_add_u32_e32 v248, 1, v248
	v_and_b32_e32 v249, 0xffc0, v248
	v_or_b32_e32 v249, v249, v250
	v_lshlrev_b32_e32 v249, 3, v249
	global_load_dwordx2 v[226:227], v249, s[82:83]
	v_add_u32_e32 v248, s10, v129
	v_add_u32_e32 v248, 2, v248
	v_and_b32_e32 v249, 0xffc0, v248
	v_or_b32_e32 v249, v249, v250
	v_lshlrev_b32_e32 v249, 3, v249
	global_load_dwordx2 v[228:229], v249, s[82:83]
	v_add_u32_e32 v248, s10, v129
	v_add_u32_e32 v248, 3, v248
	v_and_b32_e32 v249, 0xffc0, v248
	v_or_b32_e32 v249, v249, v250
	v_lshlrev_b32_e32 v249, 3, v249
	global_load_dwordx2 v[230:231], v249, s[82:83]
	v_add_u32_e32 v248, s10, v130
	v_and_b32_e32 v249, 0xffc0, v248
	v_or_b32_e32 v249, v249, v250
	v_lshlrev_b32_e32 v249, 3, v249
	global_load_dwordx2 v[232:233], v249, s[82:83]
	v_add_u32_e32 v248, s10, v130
	v_add_u32_e32 v248, 1, v248
	v_and_b32_e32 v249, 0xffc0, v248
	v_or_b32_e32 v249, v249, v250
	v_lshlrev_b32_e32 v249, 3, v249
	global_load_dwordx2 v[234:235], v249, s[82:83]
	v_add_u32_e32 v248, s10, v130
	v_add_u32_e32 v248, 2, v248
	v_and_b32_e32 v249, 0xffc0, v248
	v_or_b32_e32 v249, v249, v250
	v_lshlrev_b32_e32 v249, 3, v249
	global_load_dwordx2 v[236:237], v249, s[82:83]
	v_add_u32_e32 v248, s10, v130
	v_add_u32_e32 v248, 3, v248
	v_and_b32_e32 v249, 0xffc0, v248
	v_or_b32_e32 v249, v249, v250
	v_lshlrev_b32_e32 v249, 3, v249
	global_load_dwordx2 v[238:239], v249, s[82:83]
	v_add_u32_e32 v248, s10, v131
	v_and_b32_e32 v249, 0xffc0, v248
	v_or_b32_e32 v249, v249, v250
	v_lshlrev_b32_e32 v249, 3, v249
	global_load_dwordx2 v[240:241], v249, s[82:83]
	v_add_u32_e32 v248, s10, v131
	v_add_u32_e32 v248, 1, v248
	v_and_b32_e32 v249, 0xffc0, v248
	v_or_b32_e32 v249, v249, v250
	v_lshlrev_b32_e32 v249, 3, v249
	global_load_dwordx2 v[242:243], v249, s[82:83]
	v_add_u32_e32 v248, s10, v131
	v_add_u32_e32 v248, 2, v248
	v_and_b32_e32 v249, 0xffc0, v248
	v_or_b32_e32 v249, v249, v250
	v_lshlrev_b32_e32 v249, 3, v249
	global_load_dwordx2 v[244:245], v249, s[82:83]
	v_add_u32_e32 v248, s10, v131
	v_add_u32_e32 v248, 3, v248
	v_and_b32_e32 v249, 0xffc0, v248
	v_or_b32_e32 v249, v249, v250
	v_lshlrev_b32_e32 v249, 3, v249
	global_load_dwordx2 v[246:247], v249, s[82:83]

.Lrope_pre_skip:
	s_andn2_b64 vcc, exec, s[42:43]
	s_cbranch_vccnz .LBB0_913
	s_mov_b64 s[8:9], -1
	s_and_b64 vcc, exec, s[40:41]
	s_cbranch_vccz .LBB0_910
	v_lshlrev_b32_e32 v56, 6, v145
	s_movk_i32 s8, 0xfc0
	v_and_or_b32 v68, v56, s8, v154
	s_mov_b64 s[8:9], 0
	v_mov_b64_e32 v[86:87], v[68:69]

.LBB0_912:
	v_mov_b32_e32 v86, v184
	v_mov_b32_e32 v87, v185
	v_pk_mul_f32 v[94:95], v[84:85], v[86:87] op_sel_hi:[0,1]
	v_pk_mul_f32 v[90:91], v[84:85], v[86:87] op_sel:[1,1] op_sel_hi:[1,0]
	v_pk_fma_f32 v[84:85], v[84:85], v[86:87], v[94:95] op_sel:[1,1,0] op_sel_hi:[1,0,1] neg_lo:[0,0,1] neg_hi:[0,0,1]
	s_nop 0
	v_add_f32_e32 v84, v90, v94

.LBB0_920:
	v_mov_b32_e32 v60, v186
	v_mov_b32_e32 v61, v187
	v_pk_mul_f32 v[86:87], v[56:57], v[60:61] op_sel_hi:[0,1]
	v_pk_mul_f32 v[84:85], v[56:57], v[60:61] op_sel:[1,1] op_sel_hi:[1,0]
	v_pk_fma_f32 v[56:57], v[56:57], v[60:61], v[86:87] op_sel:[1,1,0] op_sel_hi:[1,0,1] neg_lo:[0,0,1] neg_hi:[0,0,1]
	s_nop 0
	v_add_f32_e32 v56, v84, v86

.LBB0_928:
	v_mov_b32_e32 v60, v188
	v_mov_b32_e32 v61, v189
	v_pk_mul_f32 v[96:97], v[56:57], v[60:61] op_sel_hi:[0,1]
	v_pk_mul_f32 v[84:85], v[56:57], v[60:61] op_sel:[1,1] op_sel_hi:[1,0]
	v_pk_fma_f32 v[56:57], v[56:57], v[60:61], v[96:97] op_sel:[1,1,0] op_sel_hi:[1,0,1] neg_lo:[0,0,1] neg_hi:[0,0,1]
	s_nop 0
	v_add_f32_e32 v56, v84, v96

.LBB0_936:
	v_mov_b32_e32 v58, v190
	v_mov_b32_e32 v59, v191
	v_pk_mul_f32 v[62:63], v[56:57], v[58:59] op_sel_hi:[0,1]
	v_pk_mul_f32 v[60:61], v[56:57], v[58:59] op_sel:[1,1] op_sel_hi:[1,0]
	v_pk_fma_f32 v[56:57], v[56:57], v[58:59], v[62:63] op_sel:[1,1,0] op_sel_hi:[1,0,1] neg_lo:[0,0,1] neg_hi:[0,0,1]
	s_nop 0
	v_add_f32_e32 v56, v60, v62

.LBB0_946:
	v_mov_b32_e32 v60, v192
	v_mov_b32_e32 v61, v193
	v_pk_mov_b32 v[100:101], v[56:57], v[56:57] op_sel:[1,0]
	v_mul_f32_e32 v48, v56, v60
	v_pk_mul_f32 v[100:101], v[100:101], v[60:61]
	v_pk_fma_f32 v[102:103], v[56:57], v[60:61], v[48:49] op_sel_hi:[1,1,0] neg_lo:[1,0,0] neg_hi:[1,0,0]
	v_add_f32_e32 v57, v100, v101
	s_branch .LBB0_948

.LBB0_955:
	v_mov_b32_e32 v52, v194
	v_mov_b32_e32 v53, v195
	v_pk_mov_b32 v[56:57], v[48:49], v[48:49] op_sel:[1,0]
	v_mul_f32_e32 v68, v48, v52
	v_pk_mul_f32 v[56:57], v[56:57], v[52:53]
	v_pk_fma_f32 v[52:53], v[48:49], v[52:53], v[68:69] op_sel_hi:[1,1,0] neg_lo:[1,0,0] neg_hi:[1,0,0]
	v_add_f32_e32 v49, v56, v57
	s_branch .LBB0_957

.LBB0_964:
	v_mov_b32_e32 v52, v196
	v_mov_b32_e32 v53, v197
	v_pk_mov_b32 v[102:103], v[48:49], v[48:49] op_sel:[1,0]
	v_mul_f32_e32 v50, v48, v52
	v_pk_mul_f32 v[148:149], v[102:103], v[52:53]
	v_pk_fma_f32 v[102:103], v[48:49], v[52:53], v[50:51] op_sel_hi:[1,1,0] neg_lo:[1,0,0] neg_hi:[1,0,0]
	v_add_f32_e32 v49, v148, v149
	s_branch .LBB0_966

.LBB0_973:
	v_mov_b32_e32 v50, v198
	v_mov_b32_e32 v51, v199
	v_pk_mov_b32 v[54:55], v[48:49], v[48:49] op_sel:[1,0]
	v_mul_f32_e32 v68, v48, v50
	v_pk_mul_f32 v[102:103], v[54:55], v[50:51]
	v_pk_fma_f32 v[54:55], v[48:49], v[50:51], v[68:69] op_sel_hi:[1,1,0] neg_lo:[1,0,0] neg_hi:[1,0,0]
	v_add_f32_e32 v49, v102, v103
	s_branch .LBB0_975

.LBB0_984:
	v_mov_b32_e32 v48, v200
	v_mov_b32_e32 v49, v201
	v_mul_f32_e32 v40, v101, v48
	v_pk_mul_f32 v[54:55], v[100:101], v[48:49]
	v_pk_fma_f32 v[100:101], v[100:101], v[48:49], v[40:41] op_sel:[1,0,0] op_sel_hi:[0,1,0] neg_lo:[1,0,0] neg_hi:[1,0,0]
	v_add_f32_e32 v100, v54, v55

.LBB0_992:
	v_mov_b32_e32 v40, v202
	v_mov_b32_e32 v41, v203
	v_mul_f32_e32 v68, v45, v40
	v_pk_mul_f32 v[100:101], v[44:45], v[40:41]
	v_pk_fma_f32 v[44:45], v[44:45], v[40:41], v[68:69] op_sel:[1,0,0] op_sel_hi:[0,1,0] neg_lo:[1,0,0] neg_hi:[1,0,0]
	v_add_f32_e32 v44, v100, v101

.LBB0_1000:
	v_mov_b32_e32 v44, v204
	v_mov_b32_e32 v45, v205
	v_mul_f32_e32 v42, v101, v44
	v_pk_mul_f32 v[162:163], v[100:101], v[44:45]
	v_pk_fma_f32 v[100:101], v[100:101], v[44:45], v[42:43] op_sel:[1,0,0] op_sel_hi:[0,1,0] neg_lo:[1,0,0] neg_hi:[1,0,0]
	v_add_f32_e32 v100, v162, v163

.LBB0_1008:
	v_mov_b32_e32 v42, v206
	v_mov_b32_e32 v43, v207
	v_mul_f32_e32 v68, v47, v42
	v_pk_fma_f32 v[100:101], v[46:47], v[42:43], v[68:69] op_sel:[1,0,0] op_sel_hi:[0,1,0] neg_lo:[1,0,0] neg_hi:[1,0,0]
	v_pk_mul_f32 v[42:43], v[46:47], v[42:43]
	s_nop 0
	v_add_f32_e32 v46, v42, v43
	s_branch .LBB0_1010

.LBB0_1019:
	v_mov_b32_e32 v46, v208
	v_mov_b32_e32 v47, v209
	v_pk_mul_f32 v[176:177], v[100:101], v[46:47] op_sel_hi:[0,1]
	v_pk_mul_f32 v[54:55], v[100:101], v[46:47] op_sel:[1,1] op_sel_hi:[1,0]
	v_pk_fma_f32 v[100:101], v[100:101], v[46:47], v[176:177] op_sel:[1,1,0] op_sel_hi:[1,0,1] neg_lo:[0,0,1] neg_hi:[0,0,1]
	s_nop 0
	v_add_f32_e32 v100, v54, v176

.LBB0_1027:
	v_mov_b32_e32 v32, v210
	v_mov_b32_e32 v33, v211
	v_pk_mul_f32 v[176:177], v[36:37], v[32:33] op_sel_hi:[0,1]
	v_pk_mul_f32 v[100:101], v[36:37], v[32:33] op_sel:[1,1] op_sel_hi:[1,0]
	v_pk_fma_f32 v[36:37], v[36:37], v[32:33], v[176:177] op_sel:[1,1,0] op_sel_hi:[1,0,1] neg_lo:[0,0,1] neg_hi:[0,0,1]
	s_nop 0
	v_add_f32_e32 v36, v100, v176

.LBB0_1035:
	v_mov_b32_e32 v36, v212
	v_mov_b32_e32 v37, v213
	v_pk_mul_f32 v[178:179], v[100:101], v[36:37] op_sel_hi:[0,1]
	v_pk_mul_f32 v[176:177], v[100:101], v[36:37] op_sel:[1,1] op_sel_hi:[1,0]
	v_pk_fma_f32 v[100:101], v[100:101], v[36:37], v[178:179] op_sel:[1,1,0] op_sel_hi:[1,0,1] neg_lo:[0,0,1] neg_hi:[0,0,1]
	s_nop 0
	v_add_f32_e32 v100, v176, v178

.LBB0_1043:
	v_mov_b32_e32 v34, v214
	v_mov_b32_e32 v35, v215
	v_pk_mul_f32 v[178:179], v[38:39], v[34:35] op_sel_hi:[0,1]
	v_pk_mul_f32 v[176:177], v[38:39], v[34:35] op_sel:[1,1] op_sel_hi:[1,0]
	v_pk_fma_f32 v[38:39], v[38:39], v[34:35], v[178:179] op_sel:[1,1,0] op_sel_hi:[1,0,1] neg_lo:[0,0,1] neg_hi:[0,0,1]
	s_nop 0
	v_add_f32_e32 v38, v176, v178

.LBB0_1053:
	v_mov_b32_e32 v54, v216
	v_mov_b32_e32 v55, v217
	v_pk_mul_f32 v[96:97], v[38:39], v[54:55] op_sel_hi:[0,1]
	v_pk_mul_f32 v[94:95], v[38:39], v[54:55] op_sel:[1,1] op_sel_hi:[1,0]
	v_pk_fma_f32 v[38:39], v[38:39], v[54:55], v[96:97] op_sel:[1,1,0] op_sel_hi:[1,0,1] neg_lo:[0,0,1] neg_hi:[0,0,1]
	s_nop 0
	v_add_f32_e32 v38, v94, v96

.LBB0_1061:
	v_mov_b32_e32 v28, v218
	v_mov_b32_e32 v29, v219
	v_pk_mul_f32 v[88:89], v[24:25], v[28:29] op_sel_hi:[0,1]
	v_pk_mul_f32 v[38:39], v[24:25], v[28:29] op_sel:[1,1] op_sel_hi:[1,0]
	v_pk_fma_f32 v[24:25], v[24:25], v[28:29], v[88:89] op_sel:[1,1,0] op_sel_hi:[1,0,1] neg_lo:[0,0,1] neg_hi:[0,0,1]
	s_nop 0
	v_add_f32_e32 v24, v38, v88

.LBB0_1069:
	v_mov_b32_e32 v28, v220
	v_mov_b32_e32 v29, v221
	v_pk_mul_f32 v[86:87], v[24:25], v[28:29] op_sel_hi:[0,1]
	v_pk_mul_f32 v[38:39], v[24:25], v[28:29] op_sel:[1,1] op_sel_hi:[1,0]
	v_pk_fma_f32 v[24:25], v[24:25], v[28:29], v[86:87] op_sel:[1,1,0] op_sel_hi:[1,0,1] neg_lo:[0,0,1] neg_hi:[0,0,1]
	s_nop 0
	v_add_f32_e32 v24, v38, v86

.LBB0_1077:
	v_mov_b32_e32 v26, v222
	v_mov_b32_e32 v27, v223
	v_pk_mul_f32 v[30:31], v[24:25], v[26:27] op_sel_hi:[0,1]
	v_pk_mul_f32 v[28:29], v[24:25], v[26:27] op_sel:[1,1] op_sel_hi:[1,0]
	v_pk_fma_f32 v[24:25], v[24:25], v[26:27], v[30:31] op_sel:[1,1,0] op_sel_hi:[1,0,1] neg_lo:[0,0,1] neg_hi:[0,0,1]
	s_nop 0
	v_add_f32_e32 v24, v28, v30

.LBB0_1087:
	v_mov_b32_e32 v54, v224
	v_mov_b32_e32 v55, v225
	v_pk_mul_f32 v[62:63], v[38:39], v[54:55] op_sel_hi:[0,1]
	v_pk_mul_f32 v[58:59], v[38:39], v[54:55] op_sel:[1,1] op_sel_hi:[1,0]
	v_pk_fma_f32 v[38:39], v[38:39], v[54:55], v[62:63] op_sel:[1,1,0] op_sel_hi:[1,0,1] neg_lo:[0,0,1] neg_hi:[0,0,1]
	s_nop 0
	v_add_f32_e32 v38, v58, v62

.LBB0_1095:
	v_mov_b32_e32 v20, v226
	v_mov_b32_e32 v21, v227
	v_pk_mul_f32 v[54:55], v[16:17], v[20:21] op_sel_hi:[0,1]
	v_pk_mul_f32 v[38:39], v[16:17], v[20:21] op_sel:[1,1] op_sel_hi:[1,0]
	v_pk_fma_f32 v[16:17], v[16:17], v[20:21], v[54:55] op_sel:[1,1,0] op_sel_hi:[1,0,1] neg_lo:[0,0,1] neg_hi:[0,0,1]
	s_nop 0
	v_add_f32_e32 v16, v38, v54

.LBB0_1103:
	v_mov_b32_e32 v20, v228
	v_mov_b32_e32 v21, v229
	v_pk_mul_f32 v[54:55], v[16:17], v[20:21] op_sel_hi:[0,1]
	v_pk_mul_f32 v[38:39], v[16:17], v[20:21] op_sel:[1,1] op_sel_hi:[1,0]
	v_pk_fma_f32 v[16:17], v[16:17], v[20:21], v[54:55] op_sel:[1,1,0] op_sel_hi:[1,0,1] neg_lo:[0,0,1] neg_hi:[0,0,1]
	s_nop 0
	v_add_f32_e32 v16, v38, v54

.LBB0_1111:
	v_mov_b32_e32 v18, v230
	v_mov_b32_e32 v19, v231
	v_pk_mul_f32 v[22:23], v[16:17], v[18:19] op_sel_hi:[0,1]
	v_pk_mul_f32 v[20:21], v[16:17], v[18:19] op_sel:[1,1] op_sel_hi:[1,0]
	v_pk_fma_f32 v[16:17], v[16:17], v[18:19], v[22:23] op_sel:[1,1,0] op_sel_hi:[1,0,1] neg_lo:[0,0,1] neg_hi:[0,0,1]
	s_nop 0
	v_add_f32_e32 v16, v20, v22

.LBB0_1121:
	v_mov_b32_e32 v18, v232
	v_mov_b32_e32 v19, v233
	v_pk_mul_f32 v[22:23], v[16:17], v[18:19] op_sel_hi:[0,1]
	v_pk_mul_f32 v[20:21], v[16:17], v[18:19] op_sel:[1,1] op_sel_hi:[1,0]
	v_pk_fma_f32 v[16:17], v[16:17], v[18:19], v[22:23] op_sel:[1,1,0] op_sel_hi:[1,0,1] neg_lo:[0,0,1] neg_hi:[0,0,1]
	s_nop 0
	v_add_f32_e32 v16, v20, v22

.LBB0_1129:
	v_mov_b32_e32 v12, v234
	v_mov_b32_e32 v13, v235
	v_pk_mul_f32 v[18:19], v[8:9], v[12:13] op_sel_hi:[0,1]
	v_pk_mul_f32 v[16:17], v[8:9], v[12:13] op_sel:[1,1] op_sel_hi:[1,0]
	v_pk_fma_f32 v[8:9], v[8:9], v[12:13], v[18:19] op_sel:[1,1,0] op_sel_hi:[1,0,1] neg_lo:[0,0,1] neg_hi:[0,0,1]
	s_nop 0
	v_add_f32_e32 v8, v16, v18

.LBB0_1137:
	v_mov_b32_e32 v12, v236
	v_mov_b32_e32 v13, v237
	v_pk_mul_f32 v[18:19], v[8:9], v[12:13] op_sel_hi:[0,1]
	v_pk_mul_f32 v[16:17], v[8:9], v[12:13] op_sel:[1,1] op_sel_hi:[1,0]
	v_pk_fma_f32 v[8:9], v[8:9], v[12:13], v[18:19] op_sel:[1,1,0] op_sel_hi:[1,0,1] neg_lo:[0,0,1] neg_hi:[0,0,1]
	s_nop 0
	v_add_f32_e32 v8, v16, v18

.LBB0_1145:
	v_mov_b32_e32 v10, v238
	v_mov_b32_e32 v11, v239
	v_pk_mul_f32 v[14:15], v[8:9], v[10:11] op_sel_hi:[0,1]
	v_pk_mul_f32 v[12:13], v[8:9], v[10:11] op_sel:[1,1] op_sel_hi:[1,0]
	v_pk_fma_f32 v[8:9], v[8:9], v[10:11], v[14:15] op_sel:[1,1,0] op_sel_hi:[1,0,1] neg_lo:[0,0,1] neg_hi:[0,0,1]
	s_nop 0
	v_add_f32_e32 v8, v12, v14

.LBB0_1155:
	v_mov_b32_e32 v10, v240
	v_mov_b32_e32 v11, v241
	v_pk_mul_f32 v[14:15], v[8:9], v[10:11] op_sel_hi:[0,1]
	v_pk_mul_f32 v[12:13], v[8:9], v[10:11] op_sel:[1,1] op_sel_hi:[1,0]
	v_pk_fma_f32 v[8:9], v[8:9], v[10:11], v[14:15] op_sel:[1,1,0] op_sel_hi:[1,0,1] neg_lo:[0,0,1] neg_hi:[0,0,1]
	s_nop 0
	v_add_f32_e32 v8, v12, v14

.LBB0_1163:
	v_mov_b32_e32 v4, v242
	v_mov_b32_e32 v5, v243
	v_pk_mul_f32 v[10:11], v[0:1], v[4:5] op_sel_hi:[0,1]
	v_pk_mul_f32 v[8:9], v[0:1], v[4:5] op_sel:[1,1] op_sel_hi:[1,0]
	v_pk_fma_f32 v[0:1], v[0:1], v[4:5], v[10:11] op_sel:[1,1,0] op_sel_hi:[1,0,1] neg_lo:[0,0,1] neg_hi:[0,0,1]
	s_nop 0
	v_add_f32_e32 v0, v8, v10

.LBB0_1171:
	v_mov_b32_e32 v4, v244
	v_mov_b32_e32 v5, v245
	v_pk_mul_f32 v[10:11], v[0:1], v[4:5] op_sel_hi:[0,1]
	v_pk_mul_f32 v[8:9], v[0:1], v[4:5] op_sel:[1,1] op_sel_hi:[1,0]
	v_pk_fma_f32 v[0:1], v[0:1], v[4:5], v[10:11] op_sel:[1,1,0] op_sel_hi:[1,0,1] neg_lo:[0,0,1] neg_hi:[0,0,1]
	s_nop 0
	v_add_f32_e32 v0, v8, v10

.LBB0_1179:
	v_mov_b32_e32 v2, v246
	v_mov_b32_e32 v3, v247
	v_pk_mul_f32 v[6:7], v[0:1], v[2:3] op_sel_hi:[0,1]
	v_pk_mul_f32 v[4:5], v[0:1], v[2:3] op_sel:[1,1] op_sel_hi:[1,0]
	v_pk_fma_f32 v[0:1], v[0:1], v[2:3], v[6:7] op_sel:[1,1,0] op_sel_hi:[1,0,1] neg_lo:[0,0,1] neg_hi:[0,0,1]
	s_nop 0
	v_add_f32_e32 v0, v4, v6

.LBB0_1485:
	v_readlane_b32 s1, v180, 10
	s_add_i32 s0, s0, s1
	s_mulk_i32 s0, 0xc00
	s_ashr_i32 s1, s0, 31
	v_readlane_b32 s40, v183, 1
	s_lshl_b64 s[0:1], s[0:1], 2
	v_readlane_b32 s54, v183, 15
	v_readlane_b32 s55, v183, 16
	s_add_u32 s0, s54, s0
	s_addc_u32 s1, s55, s1
	s_add_u32 s0, s0, 0x4002000
	v_or_b32_e32 v88, s20, v93
	s_addc_u32 s1, s1, 0
	s_lshl_b64 s[8:9], s[8:9], 12
	v_ashrrev_i32_e32 v89, 31, v88
	s_add_u32 s10, s10, s8
	v_lshl_add_u64 v[90:91], v[76:77], 0, v[88:89]
	s_addc_u32 s11, s11, s9
	v_lshl_add_u64 v[100:101], v[88:89], 2, s[0:1]
	v_lshlrev_b64 v[102:103], 2, v[90:91]
	v_lshl_add_u64 v[90:91], s[10:11], 0, v[102:103]
	global_load_dwordx4 v[120:123], v[100:101], off
	s_nop 0
	global_load_dwordx4 v[124:127], v[90:91], off
	s_add_u32 s8, s36, s8
	v_lshl_add_u64 v[100:101], v[78:79], 0, v[88:89]
	s_addc_u32 s9, s37, s9
	v_lshlrev_b64 v[128:129], 2, v[100:101]
	v_lshl_add_u64 v[100:101], s[8:9], 0, v[102:103]
	v_lshl_add_u64 v[102:103], s[10:11], 0, v[128:129]
	v_lshl_add_u64 v[130:131], s[8:9], 0, v[128:129]
	v_readlane_b32 s52, v183, 13
	v_readlane_b32 s53, v183, 14
	v_readlane_b32 s50, v183, 11
	v_readlane_b32 s51, v183, 12
	s_add_i32 s12, s12, s84
	v_readlane_b32 s52, v181, 60
	v_readlane_b32 s50, v180, 0
	v_readlane_b32 s53, v181, 61
	v_readlane_b32 s54, v181, 62
	v_readlane_b32 s55, v181, 63
	v_readlane_b32 s41, v183, 2
	v_readlane_b32 s42, v183, 3
	v_readlane_b32 s43, v183, 4
	v_readlane_b32 s44, v183, 5
	v_readlane_b32 s45, v183, 6
	v_readlane_b32 s46, v183, 7
	v_readlane_b32 s47, v183, 8
	v_readlane_b32 s48, v183, 9
	v_readlane_b32 s49, v183, 10
	v_readlane_b32 s51, v180, 1
	global_load_dwordx4 v[132:135], v[102:103], off
	v_lshl_add_u64 v[128:129], v[80:81], 0, v[88:89]
	v_lshlrev_b64 v[136:137], 2, v[128:129]
	v_lshl_add_u64 v[128:129], s[10:11], 0, v[136:137]
	v_lshl_add_u64 v[138:139], s[8:9], 0, v[136:137]
	global_load_dwordx4 v[140:143], v[128:129], off
	v_lshl_add_u64 v[136:137], v[82:83], 0, v[88:89]
	v_lshlrev_b64 v[144:145], 2, v[136:137]
	v_lshl_add_u64 v[136:137], s[10:11], 0, v[144:145]
	global_load_dwordx4 v[146:149], v[136:137], off
	v_or_b32_e32 v150, 16, v88
	v_ashrrev_i32_e32 v151, 31, v150
	v_lshl_add_u64 v[152:153], s[8:9], 0, v[144:145]
	v_lshl_add_u64 v[144:145], v[150:151], 2, s[0:1]
	global_load_dwordx4 v[154:157], v[144:145], off
	s_nop 0
	global_load_dwordx4 v[158:161], v[90:91], off offset:64
	global_load_dwordx4 v[162:165], v[102:103], off offset:64
	global_load_dwordx4 v[166:169], v[128:129], off offset:64
	global_load_dwordx4 v[170:173], v[136:137], off offset:64
	v_or_b32_e32 v144, 32, v88
	v_ashrrev_i32_e32 v145, 31, v144
	v_lshl_add_u64 v[150:151], v[144:145], 2, s[0:1]
	global_load_dwordx4 v[174:177], v[150:151], off
	s_nop 0
	global_load_dwordx4 v[184:187], v[90:91], off offset:128
	global_load_dwordx4 v[188:191], v[102:103], off offset:128
	global_load_dwordx4 v[192:195], v[128:129], off offset:128
	global_load_dwordx4 v[196:199], v[136:137], off offset:128
	v_or_b32_e32 v144, 48, v88
	v_ashrrev_i32_e32 v145, 31, v144
	v_lshl_add_u64 v[88:89], v[144:145], 2, s[0:1]
	v_readlane_b32 s0, v180, 7
	s_cmp_ge_i32 s12, s0
	global_load_dwordx4 v[200:203], v[88:89], off
	s_nop 0
	global_load_dwordx4 v[204:207], v[90:91], off offset:192
	global_load_dwordx4 v[88:91], v[102:103], off offset:192
	global_load_dwordx4 v[208:211], v[128:129], off offset:192
	global_load_dwordx4 v[212:215], v[136:137], off offset:192
	s_waitcnt vmcnt(0)
	v_pk_fma_f32 v[60:61], v[60:61], v[120:121], v[124:125]
	v_pk_fma_f32 v[62:63], v[62:63], v[122:123], v[126:127]
	global_store_dwordx4 v[100:101], v[60:63], off
	v_pk_fma_f32 v[56:57], v[56:57], v[120:121], v[132:133]
	v_pk_fma_f32 v[58:59], v[58:59], v[122:123], v[134:135]
	global_store_dwordx4 v[130:131], v[56:59], off
	v_pk_fma_f32 v[52:53], v[52:53], v[120:121], v[140:141]
	v_pk_fma_f32 v[54:55], v[54:55], v[122:123], v[142:143]
	global_store_dwordx4 v[138:139], v[52:55], off
	v_pk_fma_f32 v[48:49], v[48:49], v[120:121], v[146:147]
	v_pk_fma_f32 v[50:51], v[50:51], v[122:123], v[148:149]
	global_store_dwordx4 v[152:153], v[48:51], off
	v_pk_fma_f32 v[44:45], v[44:45], v[154:155], v[158:159]
	v_pk_fma_f32 v[46:47], v[46:47], v[156:157], v[160:161]
	global_store_dwordx4 v[100:101], v[44:47], off offset:64
	v_pk_fma_f32 v[40:41], v[40:41], v[154:155], v[162:163]
	v_pk_fma_f32 v[42:43], v[42:43], v[156:157], v[164:165]
	global_store_dwordx4 v[130:131], v[40:43], off offset:64
	v_pk_fma_f32 v[36:37], v[36:37], v[154:155], v[166:167]
	v_pk_fma_f32 v[38:39], v[38:39], v[156:157], v[168:169]
	global_store_dwordx4 v[138:139], v[36:39], off offset:64
	v_pk_fma_f32 v[32:33], v[32:33], v[154:155], v[170:171]
	v_pk_fma_f32 v[34:35], v[34:35], v[156:157], v[172:173]
	global_store_dwordx4 v[152:153], v[32:35], off offset:64
	v_pk_fma_f32 v[28:29], v[28:29], v[174:175], v[184:185]
	v_pk_fma_f32 v[30:31], v[30:31], v[176:177], v[186:187]
	global_store_dwordx4 v[100:101], v[28:31], off offset:128
	v_pk_fma_f32 v[24:25], v[24:25], v[174:175], v[188:189]
	v_pk_fma_f32 v[26:27], v[26:27], v[176:177], v[190:191]
	global_store_dwordx4 v[130:131], v[24:27], off offset:128
	v_pk_fma_f32 v[20:21], v[20:21], v[174:175], v[192:193]
	v_pk_fma_f32 v[22:23], v[22:23], v[176:177], v[194:195]
	global_store_dwordx4 v[138:139], v[20:23], off offset:128
	v_pk_fma_f32 v[16:17], v[16:17], v[174:175], v[196:197]
	v_pk_fma_f32 v[18:19], v[18:19], v[176:177], v[198:199]
	global_store_dwordx4 v[152:153], v[16:19], off offset:128
	v_pk_fma_f32 v[12:13], v[12:13], v[200:201], v[204:205]
	v_pk_fma_f32 v[14:15], v[14:15], v[202:203], v[206:207]
	global_store_dwordx4 v[100:101], v[12:15], off offset:192
	v_pk_fma_f32 v[8:9], v[8:9], v[200:201], v[88:89]
	v_pk_fma_f32 v[10:11], v[10:11], v[202:203], v[90:91]
	global_store_dwordx4 v[130:131], v[8:11], off offset:192
	v_pk_fma_f32 v[4:5], v[4:5], v[200:201], v[208:209]
	v_pk_fma_f32 v[6:7], v[6:7], v[202:203], v[210:211]
	global_store_dwordx4 v[138:139], v[4:7], off offset:192
	v_pk_fma_f32 v[0:1], v[0:1], v[200:201], v[212:213]
	v_pk_fma_f32 v[2:3], v[2:3], v[202:203], v[214:215]
	global_store_dwordx4 v[152:153], v[0:3], off offset:192
	s_cbranch_scc1 .LBB0_1493

.LBB0_1705:
	v_readlane_b32 s1, v180, 10
	s_add_i32 s0, s0, s1
	s_mulk_i32 s0, 0xc00
	s_ashr_i32 s1, s0, 31
	v_readlane_b32 s40, v183, 1
	s_lshl_b64 s[0:1], s[0:1], 2
	v_readlane_b32 s54, v183, 15
	v_readlane_b32 s55, v183, 16
	s_add_u32 s0, s54, s0
	s_addc_u32 s1, s55, s1
	s_add_u32 s0, s0, 0x4002000
	v_or_b32_e32 v86, s20, v91
	s_addc_u32 s1, s1, 0
	s_lshl_b64 s[8:9], s[8:9], 12
	v_ashrrev_i32_e32 v87, 31, v86
	s_add_u32 s10, s10, s8
	v_lshl_add_u64 v[88:89], v[76:77], 0, v[86:87]
	s_addc_u32 s11, s11, s9
	v_lshl_add_u64 v[98:99], v[86:87], 2, s[0:1]
	v_lshlrev_b64 v[100:101], 2, v[88:89]
	v_lshl_add_u64 v[88:89], s[10:11], 0, v[100:101]
	global_load_dwordx4 v[120:123], v[98:99], off
	s_nop 0
	global_load_dwordx4 v[124:127], v[88:89], off
	s_add_u32 s8, s36, s8
	v_lshl_add_u64 v[98:99], v[78:79], 0, v[86:87]
	s_addc_u32 s9, s37, s9
	v_lshlrev_b64 v[102:103], 2, v[98:99]
	v_lshl_add_u64 v[98:99], s[8:9], 0, v[100:101]
	v_lshl_add_u64 v[100:101], s[10:11], 0, v[102:103]
	v_lshl_add_u64 v[128:129], s[8:9], 0, v[102:103]
	v_readlane_b32 s52, v183, 13
	v_readlane_b32 s53, v183, 14
	s_add_i32 s12, s12, s84
	v_readlane_b32 s52, v181, 60
	v_readlane_b32 s53, v181, 61
	v_readlane_b32 s54, v181, 62
	v_readlane_b32 s55, v181, 63
	v_readlane_b32 s41, v183, 2
	v_readlane_b32 s42, v183, 3
	v_readlane_b32 s43, v183, 4
	v_readlane_b32 s44, v183, 5
	v_readlane_b32 s45, v183, 6
	v_readlane_b32 s46, v183, 7
	v_readlane_b32 s47, v183, 8
	v_readlane_b32 s48, v183, 9
	v_readlane_b32 s49, v183, 10
	v_readlane_b32 s50, v183, 11
	v_readlane_b32 s51, v183, 12
	global_load_dwordx4 v[130:133], v[100:101], off
	v_lshl_add_u64 v[102:103], v[80:81], 0, v[86:87]
	v_lshlrev_b64 v[134:135], 2, v[102:103]
	v_lshl_add_u64 v[102:103], s[10:11], 0, v[134:135]
	v_lshl_add_u64 v[136:137], s[8:9], 0, v[134:135]
	global_load_dwordx4 v[138:141], v[102:103], off
	v_lshl_add_u64 v[134:135], v[82:83], 0, v[86:87]
	v_lshlrev_b64 v[142:143], 2, v[134:135]
	v_lshl_add_u64 v[134:135], s[10:11], 0, v[142:143]
	global_load_dwordx4 v[144:147], v[134:135], off
	v_or_b32_e32 v148, 16, v86
	v_ashrrev_i32_e32 v149, 31, v148
	v_lshl_add_u64 v[150:151], s[8:9], 0, v[142:143]
	v_lshl_add_u64 v[142:143], v[148:149], 2, s[0:1]
	global_load_dwordx4 v[152:155], v[142:143], off
	s_nop 0
	global_load_dwordx4 v[156:159], v[88:89], off offset:64
	global_load_dwordx4 v[160:163], v[100:101], off offset:64
	global_load_dwordx4 v[164:167], v[102:103], off offset:64
	global_load_dwordx4 v[168:171], v[134:135], off offset:64
	v_or_b32_e32 v142, 32, v86
	v_ashrrev_i32_e32 v143, 31, v142
	v_lshl_add_u64 v[148:149], v[142:143], 2, s[0:1]
	global_load_dwordx4 v[172:175], v[148:149], off
	s_nop 0
	global_load_dwordx4 v[176:179], v[88:89], off offset:128
	global_load_dwordx4 v[184:187], v[100:101], off offset:128
	global_load_dwordx4 v[188:191], v[102:103], off offset:128
	global_load_dwordx4 v[192:195], v[134:135], off offset:128
	v_or_b32_e32 v142, 48, v86
	v_ashrrev_i32_e32 v143, 31, v142
	v_lshl_add_u64 v[86:87], v[142:143], 2, s[0:1]
	v_readlane_b32 s0, v180, 7
	s_cmp_ge_i32 s12, s0
	global_load_dwordx4 v[196:199], v[86:87], off
	s_nop 0
	global_load_dwordx4 v[200:203], v[88:89], off offset:192
	global_load_dwordx4 v[86:89], v[100:101], off offset:192
	global_load_dwordx4 v[204:207], v[102:103], off offset:192
	global_load_dwordx4 v[100:103], v[134:135], off offset:192
	s_waitcnt vmcnt(0)
	v_pk_fma_f32 v[60:61], v[60:61], v[120:121], v[124:125]
	v_pk_fma_f32 v[62:63], v[62:63], v[122:123], v[126:127]
	global_store_dwordx4 v[98:99], v[60:63], off
	v_pk_fma_f32 v[56:57], v[56:57], v[120:121], v[130:131]
	v_pk_fma_f32 v[58:59], v[58:59], v[122:123], v[132:133]
	global_store_dwordx4 v[128:129], v[56:59], off
	v_pk_fma_f32 v[52:53], v[52:53], v[120:121], v[138:139]
	v_pk_fma_f32 v[54:55], v[54:55], v[122:123], v[140:141]
	global_store_dwordx4 v[136:137], v[52:55], off
	v_pk_fma_f32 v[48:49], v[48:49], v[120:121], v[144:145]
	v_pk_fma_f32 v[50:51], v[50:51], v[122:123], v[146:147]
	global_store_dwordx4 v[150:151], v[48:51], off
	v_pk_fma_f32 v[44:45], v[44:45], v[152:153], v[156:157]
	v_pk_fma_f32 v[46:47], v[46:47], v[154:155], v[158:159]
	global_store_dwordx4 v[98:99], v[44:47], off offset:64
	v_pk_fma_f32 v[40:41], v[40:41], v[152:153], v[160:161]
	v_pk_fma_f32 v[42:43], v[42:43], v[154:155], v[162:163]
	global_store_dwordx4 v[128:129], v[40:43], off offset:64
	v_pk_fma_f32 v[36:37], v[36:37], v[152:153], v[164:165]
	v_pk_fma_f32 v[38:39], v[38:39], v[154:155], v[166:167]
	global_store_dwordx4 v[136:137], v[36:39], off offset:64
	v_pk_fma_f32 v[32:33], v[32:33], v[152:153], v[168:169]
	v_pk_fma_f32 v[34:35], v[34:35], v[154:155], v[170:171]
	global_store_dwordx4 v[150:151], v[32:35], off offset:64
	v_pk_fma_f32 v[28:29], v[28:29], v[172:173], v[176:177]
	v_pk_fma_f32 v[30:31], v[30:31], v[174:175], v[178:179]
	global_store_dwordx4 v[98:99], v[28:31], off offset:128
	v_pk_fma_f32 v[24:25], v[24:25], v[172:173], v[184:185]
	v_pk_fma_f32 v[26:27], v[26:27], v[174:175], v[186:187]
	global_store_dwordx4 v[128:129], v[24:27], off offset:128
	v_pk_fma_f32 v[20:21], v[20:21], v[172:173], v[188:189]
	v_pk_fma_f32 v[22:23], v[22:23], v[174:175], v[190:191]
	global_store_dwordx4 v[136:137], v[20:23], off offset:128
	v_pk_fma_f32 v[16:17], v[16:17], v[172:173], v[192:193]
	v_pk_fma_f32 v[18:19], v[18:19], v[174:175], v[194:195]
	global_store_dwordx4 v[150:151], v[16:19], off offset:128
	v_pk_fma_f32 v[12:13], v[12:13], v[196:197], v[200:201]
	v_pk_fma_f32 v[14:15], v[14:15], v[198:199], v[202:203]
	global_store_dwordx4 v[98:99], v[12:15], off offset:192
	v_pk_fma_f32 v[8:9], v[8:9], v[196:197], v[86:87]
	v_pk_fma_f32 v[10:11], v[10:11], v[198:199], v[88:89]
	global_store_dwordx4 v[128:129], v[8:11], off offset:192
	v_pk_fma_f32 v[4:5], v[4:5], v[196:197], v[204:205]
	v_pk_fma_f32 v[6:7], v[6:7], v[198:199], v[206:207]
	global_store_dwordx4 v[136:137], v[4:7], off offset:192
	v_pk_fma_f32 v[0:1], v[0:1], v[196:197], v[100:101]
	v_pk_fma_f32 v[2:3], v[2:3], v[198:199], v[102:103]
	global_store_dwordx4 v[150:151], v[0:3], off offset:192
	s_cbranch_scc1 .LBB0_1713
